# combined + spatial unit: staging loads at the unit top and counted waits so the staging barrier does not wait for the gate loads
# speedup vs baseline: 1.0102x; 1.0051x over previous
.LBB0_969:
	s_or_b64 exec, exec, s[14:15]
	s_lshl_b32 s10, s21, 7
	v_add_u32_e32 v168, s10, v136
	v_or_b32_e32 v146, s12, v198
	v_ashrrev_i32_e32 v147, 31, v146
	v_lshlrev_b64 v[148:149], 10, v[146:147]
	v_or_b32_e32 v132, s10, v198
	v_lshl_add_u64 v[148:149], s[2:3], 0, v[148:149]
	s_lshl_b32 s10, s21, 8
	v_lshl_add_u64 v[148:149], v[148:149], 0, s[10:11]
	v_readlane_b32 s36, v253, 21
	v_lshl_add_u64 v[148:149], v[148:149], 0, v[140:141]
	v_lshlrev_b32_e32 v132, 2, v132
	v_readlane_b32 s37, v253, 22
	v_lshl_add_u64 v[148:149], v[148:149], 0, v[142:143]
	v_readlane_b32 s38, v253, 23
	v_readlane_b32 s39, v253, 24
	v_readlane_b32 s40, v253, 25
	v_readlane_b32 s41, v253, 26
	global_load_dword v145, v132, s[36:37]
	global_load_dwordx2 v[162:163], v[148:149], off nt
	global_load_dwordx2 v[160:161], v[148:149], off offset:16 nt
	global_load_dwordx2 v[158:159], v[148:149], off offset:32 nt
	global_load_dwordx2 v[156:157], v[148:149], off offset:48 nt
	global_load_dwordx2 v[154:155], v[148:149], off offset:64 nt
	global_load_dwordx2 v[152:153], v[148:149], off offset:80 nt
	global_load_dwordx2 v[150:151], v[148:149], off offset:96 nt
	s_nop 0
	global_load_dwordx2 v[148:149], v[148:149], off offset:112 nt
	s_waitcnt lgkmcnt(0)
	s_add_u32 s76, s74, 0x4b00000
	s_addc_u32 s77, s75, 0
	v_lshrrev_b32_e32 v0, 6, v215
	v_lshrrev_b32_e32 v1, 5, v214
	v_and_b32_e32 v2, 31, v214
	v_lshlrev_b32_e32 v2, 4, v2
	v_lshl_add_u32 v3, v0, 4, v1
	v_lshl_add_u32 v4, v3, 9, v2
	s_lshl_b32 s10, s21, 16
	v_add_u32_e32 v4, s10, v4
	v_add_u32_e32 v5, 0x1000, v4
	v_mul_u32_u24_e32 v6, 0x210, v3
	v_add_u32_e32 v6, 0x9000, v6
	v_add_u32_e32 v6, v6, v2
	v_lshrrev_b32_e32 v7, 4, v214
	v_and_b32_e32 v8, 15, v214
	v_lshlrev_b32_e32 v8, 4, v8
	v_lshl_add_u32 v9, v0, 4, v7
	v_mul_u32_u24_e32 v10, 0x110, v9
	v_add_u32_e32 v10, 0x400, v10
	v_add_u32_e32 v10, v10, v8
	s_lshl_b32 s10, s21, 7
	v_add_u32_e32 v9, s10, v9
	v_lshlrev_b32_e32 v9, 14, v9
	s_lshl_b32 s10, s12, 1
	v_add3_u32 v9, v9, v8, s10
	v_add_u32_e32 v11, 0x10000, v9
	v_readlane_b32 s42, v253, 27
	v_readlane_b32 s43, v253, 28
	v_readlane_b32 s44, v253, 29
	v_readlane_b32 s45, v253, 30
	v_readlane_b32 s46, v253, 31
	v_readlane_b32 s47, v253, 32
	v_readlane_b32 s48, v253, 33
	v_readlane_b32 s49, v253, 34
	v_readlane_b32 s50, v253, 35
	v_readlane_b32 s51, v253, 36
	s_and_saveexec_b64 s[12:13], s[4:5]
	s_cbranch_execz .LBB0_971
	s_waitcnt vmcnt(9)
	v_mov_b32_e32 v170, v17
	v_mov_b32_e32 v171, v18
	v_mov_b32_e32 v17, v19
	v_pk_add_f32 v[16:17], v[170:171], v[16:17]
	s_nop 0
	v_add_f32_e32 v16, v16, v17
	v_fmamk_f32 v16, v16, 0x3c000000, v166
	v_rsq_f32_e32 v16, v16
	ds_write_b32 v137, v16
.LBB0_971:
	s_or_b64 exec, exec, s[12:13]
	s_waitcnt vmcnt(9)
	ds_write_b128 v6, v[216:219]
	ds_write_b128 v6, v[220:223] offset:1056
	ds_write_b128 v6, v[224:227] offset:2112
	ds_write_b128 v6, v[228:231] offset:3168
	ds_write_b128 v6, v[232:235] offset:4224
	ds_write_b128 v6, v[236:239] offset:5280
	ds_write_b128 v6, v[240:243] offset:6336
	ds_write_b128 v6, v[244:247] offset:7392
	ds_write_b128 v10, v[178:181]
	ds_write_b128 v10, v[182:185] offset:1088
	ds_write_b128 v10, v[186:189] offset:2176
	ds_write_b128 v10, v[190:193] offset:3264
	s_waitcnt lgkmcnt(0)
	s_barrier
	v_mul_u32_u24_e32 v252, 0x210, v198
	v_add_u32_e32 v252, v252, v164
	v_add_u32_e32 v252, 0x9000, v252
	v_add_u32_e32 v169, v136, v196
	v_mul_u32_u24_e32 v169, 0x110, v169
	v_lshl_add_u32 v169, v197, 2, v169
	v_add_u32_e32 v169, 0x400, v169
	ds_read_b128 v[128:131], v252
	ds_read_b128 v[124:127], v252 offset:16
	ds_read_b128 v[24:27], v252 offset:64
	ds_read_b128 v[20:23], v252 offset:80
	ds_read_b128 v[120:123], v252 offset:128
	ds_read_b128 v[116:119], v252 offset:144
	ds_read_b128 v[112:115], v252 offset:192
	ds_read_b128 v[104:107], v252 offset:208
	ds_read_b128 v[96:99], v252 offset:256
	ds_read_b128 v[92:95], v252 offset:272
	ds_read_b128 v[88:91], v252 offset:320
	ds_read_b128 v[80:83], v252 offset:336
	s_waitcnt lgkmcnt(0)
	ds_read_b128 v[72:75], v252 offset:384
	ds_read_b128 v[68:71], v252 offset:400
	ds_read_b128 v[64:67], v252 offset:448
	ds_read_b128 v[56:59], v252 offset:464
	ds_read_b128 v[12:15], v169
	ds_read_b128 v[108:111], v169 offset:32
	ds_read_b128 v[100:103], v169 offset:64
	ds_read_b128 v[84:87], v169 offset:96
	ds_read_b128 v[76:79], v169 offset:128
	ds_read_b128 v[60:63], v169 offset:160
	ds_read_b128 v[8:11], v169 offset:192
	ds_read_b128 v[4:7], v169 offset:224
	s_waitcnt lgkmcnt(0)
	ds_read_b128 v[0:3], v169 offset:8704
	ds_read_b128 v[52:55], v169 offset:8736
	ds_read_b128 v[48:51], v169 offset:8768
	ds_read_b128 v[44:47], v169 offset:8800
	ds_read_b128 v[40:43], v169 offset:8832
	ds_read_b128 v[36:39], v169 offset:8864
	ds_read_b128 v[32:35], v169 offset:8896
	ds_read_b128 v[28:31], v169 offset:8928
	v_or_b32_e32 v252, v168, v197
	v_lshlrev_b32_e32 v252, 2, v252
	global_load_dwordx4 v[216:219], v252, s[24:25]
	global_load_dwordx4 v[220:223], v252, s[24:25] offset:32
	global_load_dwordx4 v[224:227], v252, s[24:25] offset:64
	global_load_dwordx4 v[228:231], v252, s[24:25] offset:96
	global_load_dwordx4 v[232:235], v252, s[24:25] offset:128
	global_load_dwordx4 v[236:239], v252, s[24:25] offset:160
	global_load_dwordx4 v[240:243], v252, s[24:25] offset:192
	global_load_dwordx4 v[244:247], v252, s[24:25] offset:224
	global_load_dwordx4 v[178:181], v252, s[40:41]
	global_load_dwordx4 v[182:185], v252, s[40:41] offset:32
	global_load_dwordx4 v[186:189], v252, s[40:41] offset:64
	global_load_dwordx4 v[190:193], v252, s[40:41] offset:96
	global_load_dwordx4 v[200:203], v252, s[40:41] offset:128
	global_load_dwordx4 v[204:207], v252, s[40:41] offset:160
	global_load_dwordx4 v[208:211], v252, s[40:41] offset:192
	global_load_dwordx4 v[248:251], v252, s[40:41] offset:224
	s_waitcnt lgkmcnt(0)
	ds_read_b128 v[16:19], v164
	ds_read_b128 v[170:173], v164 offset:16
	v_readlane_b32 s36, v253, 5
	v_readlane_b32 s44, v253, 13
	v_readlane_b32 s45, v253, 14
	s_waitcnt lgkmcnt(1)
	v_mul_f32_e32 v16, v128, v16
	s_waitcnt lgkmcnt(0)
	v_mul_f32_e32 v128, v124, v170
	v_mul_f32_e32 v17, v129, v17
	v_mul_f32_e32 v129, v125, v171
	v_mul_f32_e32 v18, v130, v18
	v_mul_f32_e32 v130, v126, v172
	v_mul_f32_e32 v19, v131, v19
	v_mul_f32_e32 v127, v127, v173
	v_cvt_pk_bf16_f32 v124, v16, v17
	v_cvt_pk_bf16_f32 v125, v18, v19
	v_cvt_pk_bf16_f32 v126, v128, v129
	v_cvt_pk_bf16_f32 v127, v130, v127
	ds_read_b128 v[16:19], v164 offset:64
	ds_read_b128 v[128:131], v164 offset:80
	v_readlane_b32 s46, v253, 15
	v_readlane_b32 s47, v253, 16
	v_readlane_b32 s48, v253, 17
	s_waitcnt lgkmcnt(1)
	v_mul_f32_e32 v16, v24, v16
	s_waitcnt lgkmcnt(0)
	v_mul_f32_e32 v20, v20, v128
	v_mul_f32_e32 v17, v25, v17
	v_mul_f32_e32 v21, v21, v129
	v_mul_f32_e32 v18, v26, v18
	v_mul_f32_e32 v22, v22, v130
	v_mul_f32_e32 v19, v27, v19
	v_mul_f32_e32 v23, v23, v131
	v_cvt_pk_bf16_f32 v128, v16, v17
	v_cvt_pk_bf16_f32 v129, v18, v19
	v_cvt_pk_bf16_f32 v130, v20, v21
	v_cvt_pk_bf16_f32 v131, v22, v23
	v_mfma_f32_32x32x16_bf16 v[12:27], v[12:15], v[124:127], 0
	ds_read_b128 v[170:173], v164 offset:128
	ds_read_b128 v[174:177], v164 offset:144
	v_readlane_b32 s49, v253, 18
	s_mov_b64 s[24:25], s[44:45]
	s_mov_b64 s[28:29], s[48:49]
	s_waitcnt lgkmcnt(1)
	v_mul_f32_e32 v120, v120, v170
	s_waitcnt lgkmcnt(0)
	v_mul_f32_e32 v132, v116, v174
	v_mul_f32_e32 v116, v121, v171
	v_mfma_f32_32x32x16_bf16 v[12:27], v[108:111], v[128:131], v[12:27]
	v_mul_f32_e32 v121, v117, v175
	v_mul_f32_e32 v117, v122, v172
	v_mul_f32_e32 v122, v118, v176
	v_mul_f32_e32 v118, v123, v173
	v_mul_f32_e32 v119, v119, v177
	v_cvt_pk_bf16_f32 v116, v120, v116
	v_cvt_pk_bf16_f32 v117, v117, v118
	v_cvt_pk_bf16_f32 v118, v132, v121
	v_cvt_pk_bf16_f32 v119, v122, v119
	ds_read_b128 v[120:123], v164 offset:192
	ds_read_b128 v[170:173], v164 offset:208
	v_mfma_f32_32x32x16_bf16 v[12:27], v[100:103], v[116:119], v[12:27]
	v_readlane_b32 s37, v253, 6
	v_readlane_b32 s38, v253, 7
	s_waitcnt lgkmcnt(1)
	v_mul_f32_e32 v108, v112, v120
	s_waitcnt lgkmcnt(0)
	v_mul_f32_e32 v109, v104, v170
	v_mul_f32_e32 v104, v113, v121
	v_mul_f32_e32 v110, v105, v171
	v_mul_f32_e32 v105, v114, v122
	v_mul_f32_e32 v111, v106, v172
	v_mul_f32_e32 v106, v115, v123
	v_mul_f32_e32 v107, v107, v173
	v_cvt_pk_bf16_f32 v104, v108, v104
	v_cvt_pk_bf16_f32 v105, v105, v106
	v_cvt_pk_bf16_f32 v106, v109, v110
	v_cvt_pk_bf16_f32 v107, v111, v107
	ds_read_b128 v[108:111], v164 offset:256
	ds_read_b128 v[112:115], v164 offset:272
	v_mfma_f32_32x32x16_bf16 v[12:27], v[84:87], v[104:107], v[12:27]
	v_readlane_b32 s39, v253, 8
	v_readlane_b32 s40, v253, 9
	s_waitcnt lgkmcnt(1)
	v_mul_f32_e32 v96, v96, v108
	s_waitcnt lgkmcnt(0)
	v_mul_f32_e32 v100, v92, v112
	v_mul_f32_e32 v92, v97, v109
	v_mul_f32_e32 v97, v93, v113
	v_mul_f32_e32 v93, v98, v110
	v_mul_f32_e32 v98, v94, v114
	v_mul_f32_e32 v94, v99, v111
	v_mul_f32_e32 v95, v95, v115
	v_cvt_pk_bf16_f32 v92, v96, v92
	v_cvt_pk_bf16_f32 v93, v93, v94
	v_cvt_pk_bf16_f32 v94, v100, v97
	v_cvt_pk_bf16_f32 v95, v98, v95
	ds_read_b128 v[96:99], v164 offset:320
	ds_read_b128 v[100:103], v164 offset:336
	v_mfma_f32_32x32x16_bf16 v[12:27], v[76:79], v[92:95], v[12:27]
	v_readlane_b32 s41, v253, 10
	v_readlane_b32 s42, v253, 11
	s_waitcnt lgkmcnt(1)
	v_mul_f32_e32 v84, v88, v96
	s_waitcnt lgkmcnt(0)
	v_mul_f32_e32 v85, v80, v100
	v_mul_f32_e32 v80, v89, v97
	v_mul_f32_e32 v86, v81, v101
	v_mul_f32_e32 v81, v90, v98
	v_mul_f32_e32 v87, v82, v102
	v_mul_f32_e32 v82, v91, v99
	v_mul_f32_e32 v83, v83, v103
	v_cvt_pk_bf16_f32 v80, v84, v80
	v_cvt_pk_bf16_f32 v81, v81, v82
	v_cvt_pk_bf16_f32 v82, v85, v86
	v_cvt_pk_bf16_f32 v83, v87, v83
	ds_read_b128 v[84:87], v164 offset:384
	ds_read_b128 v[88:91], v164 offset:400
	v_mfma_f32_32x32x16_bf16 v[12:27], v[60:63], v[80:83], v[12:27]
	v_readlane_b32 s43, v253, 12
	v_readlane_b32 s50, v253, 19
	s_waitcnt lgkmcnt(1)
	v_mul_f32_e32 v72, v72, v84
	s_waitcnt lgkmcnt(0)
	v_mul_f32_e32 v76, v68, v88
	v_mul_f32_e32 v68, v73, v85
	v_mul_f32_e32 v73, v69, v89
	v_mul_f32_e32 v69, v74, v86
	v_mul_f32_e32 v74, v70, v90
	v_mul_f32_e32 v70, v75, v87
	v_mul_f32_e32 v71, v71, v91
	v_cvt_pk_bf16_f32 v68, v72, v68
	v_cvt_pk_bf16_f32 v69, v69, v70
	v_cvt_pk_bf16_f32 v70, v76, v73
	v_cvt_pk_bf16_f32 v71, v74, v71
	ds_read_b128 v[72:75], v164 offset:448
	ds_read_b128 v[76:79], v164 offset:464
	v_readlane_b32 s51, v253, 20
	s_mov_b64 s[26:27], s[46:47]
	v_readlane_b32 s36, v253, 21
	s_waitcnt lgkmcnt(1)
	v_mul_f32_e32 v60, v64, v72
	s_waitcnt lgkmcnt(0)
	v_mul_f32_e32 v56, v56, v76
	v_mul_f32_e32 v61, v65, v73
	v_mul_f32_e32 v57, v57, v77
	v_mul_f32_e32 v62, v66, v74
	v_mul_f32_e32 v63, v58, v78
	v_mul_f32_e32 v64, v67, v75
	v_mul_f32_e32 v65, v59, v79
	v_cvt_pk_bf16_f32 v58, v60, v61
	v_cvt_pk_bf16_f32 v59, v62, v64
	v_cvt_pk_bf16_f32 v60, v56, v57
	v_or_b32_e32 v56, v168, v197
	v_lshlrev_b32_e32 v66, 2, v56
	v_cvt_pk_bf16_f32 v61, v63, v65
	v_readlane_b32 s40, v253, 25
	v_readlane_b32 s41, v253, 26
	v_mfma_f32_32x32x16_bf16 v[12:27], v[8:11], v[68:71], v[12:27]
	v_lshlrev_b32_e32 v132, 1, v56
	s_waitcnt vmcnt(16)
	v_lshlrev_b32_e32 v79, 16, v160
	v_and_b32_e32 v84, 0xffff0000, v160
	v_lshlrev_b32_e32 v85, 16, v161
	v_and_b32_e32 v86, 0xffff0000, v161
	v_readlane_b32 s37, v253, 22
	v_mfma_f32_32x32x16_bf16 v[12:27], v[4:7], v[58:61], v[12:27]
	v_lshlrev_b32_e32 v6, 16, v162
	v_lshlrev_b64 v[4:5], 11, v[146:147]
	v_lshl_add_u64 v[4:5], s[8:9], 0, v[4:5]
	v_lshl_add_u64 v[56:57], v[4:5], 0, v[132:133]
	v_readlane_b32 s38, v253, 23
	v_readlane_b32 s39, v253, 24
	v_readlane_b32 s42, v253, 27
	v_readlane_b32 s43, v253, 28
	v_readlane_b32 s44, v253, 29
	v_readlane_b32 s45, v253, 30
	v_readlane_b32 s46, v253, 31
	v_readlane_b32 s47, v253, 32
	v_readlane_b32 s48, v253, 33
	v_readlane_b32 s49, v253, 34
	v_readlane_b32 s50, v253, 35
	v_readlane_b32 s51, v253, 36
	s_waitcnt vmcnt(0)
	v_fma_f32 v7, v12, v216, v145
	v_mul_f32_e32 v67, v7, v6
	v_and_b32_e32 v6, 0xffff0000, v162
	v_fma_f32 v7, v13, v217, v145
	v_mul_f32_e32 v76, v7, v6
	v_lshlrev_b32_e32 v6, 16, v163
	v_fma_f32 v7, v14, v218, v145
	v_mul_f32_e32 v77, v7, v6
	v_and_b32_e32 v6, 0xffff0000, v163
	v_fma_f32 v7, v15, v219, v145
	v_mul_f32_e32 v78, v7, v6
	v_mul_f32_e32 v6, v178, v67
	v_mul_f32_e32 v7, v179, v76
	v_cvt_pk_bf16_f32 v6, v6, v7
	v_mul_f32_e32 v7, v180, v77
	v_mul_f32_e32 v8, v181, v78
	v_cvt_pk_bf16_f32 v7, v7, v8
	global_store_dwordx2 v[56:57], v[6:7], off offset:1024
	v_mfma_f32_32x32x16_bf16 v[0:15], v[0:3], v[124:127], 0
	v_fma_f32 v16, v16, v220, v145
	v_mfma_f32_32x32x16_bf16 v[0:15], v[52:55], v[128:131], v[0:15]
	v_fma_f32 v17, v17, v221, v145
	v_fma_f32 v18, v18, v222, v145
	v_fma_f32 v19, v19, v223, v145
	v_mul_f32_e32 v52, v16, v79
	v_mul_f32_e32 v53, v17, v84
	v_mul_f32_e32 v54, v18, v85
	v_mul_f32_e32 v55, v19, v86
	v_mul_f32_e32 v16, v182, v52
	v_mul_f32_e32 v17, v183, v53
	v_mul_f32_e32 v18, v184, v54
	v_mul_f32_e32 v19, v185, v55
	v_cvt_pk_bf16_f32 v16, v16, v17
	v_cvt_pk_bf16_f32 v17, v18, v19
	global_store_dwordx2 v[56:57], v[16:17], off offset:1040
	v_mfma_f32_32x32x16_bf16 v[0:15], v[48:51], v[116:119], v[0:15]
	v_lshlrev_b32_e32 v62, 16, v158
	v_and_b32_e32 v63, 0xffff0000, v158
	v_lshlrev_b32_e32 v64, 16, v159
	v_and_b32_e32 v65, 0xffff0000, v159
	v_fma_f32 v16, v20, v224, v145
	v_fma_f32 v17, v21, v225, v145
	v_mfma_f32_32x32x16_bf16 v[0:15], v[44:47], v[104:107], v[0:15]
	v_fma_f32 v18, v22, v226, v145
	v_fma_f32 v19, v23, v227, v145
	v_mul_f32_e32 v44, v16, v62
	v_mul_f32_e32 v45, v17, v63
	v_mul_f32_e32 v46, v18, v64
	v_mul_f32_e32 v47, v19, v65
	v_mul_f32_e32 v16, v186, v44
	v_mul_f32_e32 v17, v187, v45
	v_mul_f32_e32 v18, v188, v46
	v_mul_f32_e32 v19, v189, v47
	v_cvt_pk_bf16_f32 v16, v16, v17
	v_cvt_pk_bf16_f32 v17, v18, v19
	global_store_dwordx2 v[56:57], v[16:17], off offset:1056
	v_mfma_f32_32x32x16_bf16 v[0:15], v[40:43], v[92:95], v[0:15]
	v_lshlrev_b32_e32 v40, 16, v156
	v_and_b32_e32 v41, 0xffff0000, v156
	v_lshlrev_b32_e32 v42, 16, v157
	v_and_b32_e32 v43, 0xffff0000, v157
	v_fma_f32 v16, v24, v228, v145
	v_fma_f32 v17, v25, v229, v145
	v_fma_f32 v18, v26, v230, v145
	v_fma_f32 v19, v27, v231, v145
	v_mul_f32_e32 v24, v16, v40
	v_mul_f32_e32 v25, v17, v41
	v_mul_f32_e32 v26, v18, v42
	v_mul_f32_e32 v27, v19, v43
	v_mul_f32_e32 v16, v190, v24
	v_mul_f32_e32 v17, v191, v25
	v_mul_f32_e32 v18, v192, v26
	v_mul_f32_e32 v19, v193, v27
	v_cvt_pk_bf16_f32 v16, v16, v17
	v_cvt_pk_bf16_f32 v17, v18, v19
	global_store_dwordx2 v[56:57], v[16:17], off offset:1072
	v_mfma_f32_32x32x16_bf16 v[0:15], v[36:39], v[80:83], v[0:15]
	v_mul_f32_e32 v25, v25, v25
	v_mul_f32_e32 v27, v27, v27
	v_fmac_f32_e32 v25, v24, v24
	v_fmac_f32_e32 v27, v26, v26
	v_add_f32_e32 v24, v25, v27
	v_mfma_f32_32x32x16_bf16 v[0:15], v[32:35], v[68:71], v[0:15]
	v_lshlrev_b32_e32 v32, 16, v154
	v_and_b32_e32 v33, 0xffff0000, v154
	v_lshlrev_b32_e32 v34, 16, v155
	v_and_b32_e32 v35, 0xffff0000, v155
	v_mfma_f32_32x32x16_bf16 v[0:15], v[28:31], v[58:61], v[0:15]
	s_nop 11
	v_fma_f32 v0, v0, v232, v145
	v_fma_f32 v1, v1, v233, v145
	v_fma_f32 v2, v2, v234, v145
	v_fma_f32 v3, v3, v235, v145
	v_mul_f32_e32 v28, v0, v32
	v_mul_f32_e32 v29, v1, v33
	v_mul_f32_e32 v30, v2, v34
	v_mul_f32_e32 v31, v3, v35
	v_mul_f32_e32 v0, v200, v28
	v_mul_f32_e32 v1, v201, v29
	v_mul_f32_e32 v2, v202, v30
	v_mul_f32_e32 v3, v203, v31
	v_cvt_pk_bf16_f32 v0, v0, v1
	v_cvt_pk_bf16_f32 v1, v2, v3
	global_store_dwordx2 v[56:57], v[0:1], off offset:1088
	v_lshlrev_b32_e32 v20, 16, v152
	v_and_b32_e32 v21, 0xffff0000, v152
	v_lshlrev_b32_e32 v22, 16, v153
	v_and_b32_e32 v23, 0xffff0000, v153
	v_and_b32_e32 v33, 64, v167
	v_xor_b32_e32 v32, 32, v167
	v_add_u32_e32 v33, 64, v33
	v_cmp_lt_i32_e32 vcc, v32, v33
	v_mul_f32_e32 v33, v76, v76
	v_mul_f32_e32 v34, v78, v78
	v_fmac_f32_e32 v33, v67, v67
	v_fmac_f32_e32 v34, v77, v77
	v_add_f32_e32 v33, v33, v34
	v_mul_f32_e32 v34, v53, v53
	v_mul_f32_e32 v35, v55, v55
	v_fmac_f32_e32 v34, v52, v52
	v_fmac_f32_e32 v35, v54, v54
	v_add_f32_e32 v34, v34, v35
	v_add_f32_e32 v33, v33, v34
	v_mul_f32_e32 v34, v45, v45
	v_mul_f32_e32 v35, v47, v47
	v_fmac_f32_e32 v34, v44, v44
	v_fmac_f32_e32 v35, v46, v46
	v_add_f32_e32 v34, v34, v35
	v_mul_f32_e32 v25, v29, v29
	v_mul_f32_e32 v26, v31, v31
	v_add_f32_e32 v33, v33, v34
	v_fmac_f32_e32 v25, v28, v28
	v_fmac_f32_e32 v26, v30, v30
	v_add_f32_e32 v24, v33, v24
	v_add_f32_e32 v25, v25, v26
	v_add_f32_e32 v24, v24, v25
	v_cndmask_b32_e32 v32, v167, v32, vcc
	v_fma_f32 v0, v4, v236, v145
	v_fma_f32 v1, v5, v237, v145
	v_fma_f32 v2, v6, v238, v145
	v_fma_f32 v3, v7, v239, v145
	v_mul_f32_e32 v20, v0, v20
	v_mul_f32_e32 v21, v1, v21
	v_mul_f32_e32 v22, v2, v22
	v_mul_f32_e32 v23, v3, v23
	v_mul_f32_e32 v0, v204, v20
	v_mul_f32_e32 v1, v205, v21
	v_mul_f32_e32 v2, v206, v22
	v_mul_f32_e32 v3, v207, v23
	v_cvt_pk_bf16_f32 v0, v0, v1
	v_cvt_pk_bf16_f32 v1, v2, v3
	global_store_dwordx2 v[56:57], v[0:1], off offset:1104
	v_lshlrev_b32_e32 v16, 16, v150
	v_and_b32_e32 v17, 0xffff0000, v150
	v_lshlrev_b32_e32 v18, 16, v151
	v_and_b32_e32 v19, 0xffff0000, v151
	v_mul_f32_e32 v21, v21, v21
	v_mul_f32_e32 v23, v23, v23
	v_fmac_f32_e32 v21, v20, v20
	v_fmac_f32_e32 v23, v22, v22
	v_add_f32_e32 v20, v21, v23
	v_add_f32_e32 v20, v24, v20
	v_fma_f32 v0, v8, v240, v145
	v_fma_f32 v1, v9, v241, v145
	v_fma_f32 v2, v10, v242, v145
	v_fma_f32 v3, v11, v243, v145
	v_mul_f32_e32 v8, v0, v16
	v_mul_f32_e32 v9, v1, v17
	v_mul_f32_e32 v10, v2, v18
	v_mul_f32_e32 v11, v3, v19
	v_mul_f32_e32 v0, v208, v8
	v_mul_f32_e32 v1, v209, v9
	v_mul_f32_e32 v2, v210, v10
	v_mul_f32_e32 v3, v211, v11
	v_cvt_pk_bf16_f32 v0, v0, v1
	v_cvt_pk_bf16_f32 v1, v2, v3
	global_store_dwordx2 v[56:57], v[0:1], off offset:1120
	v_mul_f32_e32 v9, v9, v9
	v_mul_f32_e32 v11, v11, v11
	v_and_b32_e32 v17, 0xffff0000, v148
	v_and_b32_e32 v19, 0xffff0000, v149
	v_fmac_f32_e32 v9, v8, v8
	v_fmac_f32_e32 v11, v10, v10
	v_lshlrev_b32_e32 v16, 16, v148
	v_lshlrev_b32_e32 v18, 16, v149
	v_add_f32_e32 v8, v9, v11
	v_add_f32_e32 v8, v20, v8
	v_fma_f32 v0, v12, v244, v145
	v_fma_f32 v1, v13, v245, v145
	v_fma_f32 v2, v14, v246, v145
	v_fmac_f32_e32 v145, v15, v247
	v_mul_f32_e32 v1, v1, v17
	v_mul_f32_e32 v9, v145, v19
	v_mul_f32_e32 v0, v0, v16
	v_mul_f32_e32 v3, v2, v18
	v_mul_f32_e32 v10, v1, v1
	v_mul_f32_e32 v11, v9, v9
	v_fmac_f32_e32 v10, v0, v0
	v_fmac_f32_e32 v11, v3, v3
	v_mul_f32_e32 v2, v248, v0
	v_mul_f32_e32 v1, v249, v1
	v_add_f32_e32 v0, v10, v11
	v_cvt_pk_bf16_f32 v2, v2, v1
	v_add_f32_e32 v0, v8, v0
	v_lshlrev_b32_e32 v1, 2, v32
	ds_bpermute_b32 v1, v1, v0
	v_mul_f32_e32 v3, v250, v3
	v_mul_f32_e32 v4, v251, v9
	v_cvt_pk_bf16_f32 v3, v3, v4
	global_store_dwordx2 v[56:57], v[2:3], off offset:1136
	s_and_saveexec_b64 s[12:13], s[0:1]
	s_cbranch_execz .LBB0_966
	v_lshlrev_b64 v[2:3], 5, v[146:147]
	v_lshl_add_u64 v[2:3], s[6:7], 0, v[2:3]
	s_lshl_b32 s10, s21, 3
	v_lshl_add_u64 v[2:3], v[2:3], 0, s[10:11]
	v_mov_b32_e32 v145, v133
	v_lshl_add_u64 v[2:3], v[2:3], 0, v[144:145]
	s_waitcnt lgkmcnt(0)
	v_add_f32_e32 v0, v0, v1
	global_store_dword v[2:3], v0, off
	s_branch .LBB0_966
